# RT1: P11 cnorm loop loads the 4 rotary table vectors on lanes 16..19 only (the lanes that use them) instead of all 64 lanes
# speedup vs baseline: 1.0017x; 1.0004x over previous
; #define GAS __attribute__((address_space(1)))
; __device__ __forceinline__ void cnorm_phase(Frame& F) {
;     ...
;         const bool lat = m < ML; const int t = m & (SEQ - 1); const int prow = t >> 6, pcol = t & 63;
;         const int pos = (lane & 2) ? pcol : prow; const float* cs = rt + pos * 8;
;         const f32x4 c0 = *(const GAS f32x4*)(cs), c1 = *(const GAS f32x4*)(cs + 4), sa = *(const GAS f32x4*)(cs + 1024), sb = *(const GAS f32x4*)(cs + 1028);
;         v4u n0 = {0u, 0u, 0u, 0u}, n1 = {0u, 0u, 0u, 0u};
;         if (m + NGW < MR) { const GAS v4u* rowp = (const GAS v4u*)(CQKV + (size_t)(m + NGW) * NCIN); n0 = rowp[lane]; if (lane < 32) n1 = rowp[64 + lane]; }
.LBB0_118:
	s_mov_b64 s[98:99], exec
	s_mov_b64 exec, s[20:21]
	s_bfe_u32 s1, s0, 0x70006
	s_and_b32 s24, s0, 63
	v_mov_b32_e32 v0, s24
	v_mov_b32_e32 v18, s1
	v_cndmask_b32_e64 v0, v0, v18, s[16:17]
	v_lshlrev_b32_e32 v0, 5, v0
	v_lshl_add_u64 v[18:19], s[2:3], 0, v[0:1]
	s_mov_b64 s[24:25], 0x1000
	v_lshl_add_u64 v[20:21], v[18:19], 0, s[24:25]
	v_add_co_u32_e32 v18, vcc, 0x1000, v18
	global_load_dwordx4 v[26:29], v0, s[2:3] offset:16
	global_load_dwordx4 v[30:33], v0, s[2:3]
	v_addc_co_u32_e32 v19, vcc, 0, v19, vcc
	global_load_dwordx4 v[38:41], v[18:19], off
	global_load_dwordx4 v[34:37], v[20:21], off offset:16
	s_mov_b64 exec, s[98:99]
	s_add_i32 s26, s0, s28
	s_cmpk_gt_i32 s26, 0x41ff
	s_cselect_b64 s[40:41], -1, 0
	s_and_b64 vcc, exec, s[40:41]
	s_cbranch_vccnz .LBB0_122
	v_lshl_add_u64 v[56:57], s[38:39], 0, v[50:51]
	v_add_co_u32_e32 v18, vcc, 0x5400000, v56
	v_mov_b32_e32 v25, 0
	s_nop 0
	v_addc_co_u32_e32 v19, vcc, 0, v57, vcc
	global_load_dwordx4 v[18:21], v[18:19], off
	v_mov_b32_e32 v24, 0
	v_mov_b32_e32 v23, 0
	v_mov_b32_e32 v22, 0
	s_and_saveexec_b64 s[24:25], s[14:15]
	s_cbranch_execz .LBB0_121
	v_add_co_u32_e32 v22, vcc, 0x5400000, v56
	s_nop 1
	v_addc_co_u32_e32 v23, vcc, 0, v57, vcc
	global_load_dwordx4 v[22:25], v[22:23], off offset:1024

;     ...
;     for (int i = F.tid; i < 1024; i += NWAVES * 64) {
;         gl[i] = gw_[i];
; #pragma unroll
;         for (int cnd = 0; cnd < 3; ++cnd) {
;             float sh, sc;
;             if (from_partials) { sh = ada_b[layer * 6144 + offsh + i]; sc = ada_b[layer * 6144 + offsc + i];
;                 float ph[ADA_KS], pc[ADA_KS];
; #pragma unroll
;                 for (int ks = 0; ks < ADA_KS; ++ks) { const float* p = modp + ((size_t)(ks * 2 + layer) * 3 + cnd) * 6144; ph[ks] = p[offsh + i]; pc[ks] = p[offsc + i]; }
; #pragma unroll
;                 for (int ks = 0; ks < ADA_KS; ++ks) { sh += ph[ks]; sc += pc[ks]; } }
;             else { sh = mod[(layer * 3 + cnd) * 6144 + offsh + i]; sc = mod[(layer * 3 + cnd) * 6144 + offsc + i]; }
;             scl[cnd * 1024 + i] = 1.f + sc; shl[cnd * 1024 + i] = sh;
;         }
;     }
.LBB0_153:
	v_lshlrev_b32_e32 v220, 2, v2
	v_lshlrev_b32_e32 v221, 2, v3
	global_load_dword v236, v220, s[4:5]
	global_load_dword v237, v221, s[4:5]
	v_add_u32_e32 v222, s12, v220
	v_add_u32_e32 v223, s12, v221
	global_load_dword v228, v222, s[8:9] offset:-4096
	global_load_dword v229, v223, s[8:9] offset:-4096
	global_load_dword v230, v222, s[8:9]
	global_load_dword v231, v223, s[8:9]
	v_add_u32_e32 v222, s13, v220
	v_add_u32_e32 v223, s13, v221
	global_load_dword v232, v222, s[8:9] offset:-4096
	global_load_dword v233, v223, s[8:9] offset:-4096
	global_load_dword v234, v222, s[8:9]
	global_load_dword v235, v223, s[8:9]
	v_add_u32_e32 v222, s14, v220
	v_add_u32_e32 v223, s14, v221
	global_load_dword v238, v222, s[8:9] offset:-4096
	global_load_dword v239, v223, s[8:9] offset:-4096
	global_load_dword v240, v222, s[8:9]
	global_load_dword v241, v223, s[8:9]
	v_add_u32_e32 v7, -2, v7
	v_add_u32_e32 v224, 0x400, v2
	v_add_u32_e32 v225, 0x400, v3
	v_lshl_add_u32 v226, v224, 2, 0
	v_lshl_add_u32 v227, v225, 2, 0
	v_cmp_eq_u32_e32 vcc, 0, v7
	s_or_b64 s[10:11], vcc, s[10:11]
	s_waitcnt vmcnt(0)
	ds_write2st64_b32 v8, v236, v237 offset1:8
	v_add_f32_e32 v230, 1.0, v230
	v_add_f32_e32 v231, 1.0, v231
	ds_write2st64_b32 v8, v230, v231 offset0:16 offset1:24
	ds_write2st64_b32 v8, v228, v229 offset0:64 offset1:72
	v_add_f32_e32 v234, 1.0, v234
	v_add_f32_e32 v235, 1.0, v235
	ds_write_b32 v226, v234 offset:4096
	ds_write_b32 v227, v235 offset:4096
	ds_write_b32 v226, v232 offset:16384
	ds_write_b32 v227, v233 offset:16384
	v_add_f32_e32 v240, 1.0, v240
	v_add_f32_e32 v241, 1.0, v241
	ds_write_b32 v220, v240 offset:12288
	ds_write_b32 v221, v241 offset:12288
	ds_write_b32 v220, v238 offset:24576
	ds_write_b32 v221, v239 offset:24576
	v_add_u32_e32 v8, 0x1000, v8
	v_mov_b32_e32 v2, v224
	v_mov_b32_e32 v3, v225
	s_andn2_b64 exec, exec, s[10:11]
	s_cbranch_execnz .LBB0_153
	s_nop 0
	s_nop 0
	s_or_b64 exec, exec, s[10:11]
	v_cmp_ne_u32_e32 vcc, v0, v6
	v_lshl_add_u32 v2, v6, 9, v170
	s_orn2_b64 s[8:9], vcc, exec
